# prologue f32 activation rows also nt
# baseline (speedup 1.0000x reference)
.LBB0_73:
	s_cmpk_gt_i32 s34, 0x3fff
	s_mov_b64 s[24:25], -1
	s_cbranch_scc0 .LBB0_83
	s_cmpk_gt_u32 s34, 0x407f
	s_cbranch_scc0 .LBB0_78
	v_mov_b32_e32 v27, s3
	s_waitcnt lgkmcnt(0)
	ds_read_b64 v[28:29], v27
	s_add_i32 s12, s34, 0xffffbf80
	s_lshl_b64 s[24:25], s[12:13], 12
	v_cmp_lt_i32_e32 vcc, v21, v20
	s_waitcnt lgkmcnt(0)
	v_readfirstlane_b32 s17, v28
	v_readfirstlane_b32 s35, v29
	s_add_u32 s24, s17, s24
	s_addc_u32 s25, s35, s25
	v_lshl_add_u64 v[40:41], s[24:25], 0, v[2:3]
	global_load_dwordx4 v[28:31], v[40:41], off nt
	s_lshl_b64 s[24:25], s[12:13], 11
	v_lshl_add_u64 v[44:45], v[4:5], 0, s[24:25]
	s_waitcnt vmcnt(0) lgkmcnt(0)
	v_bfe_u32 v27, v28, 16, 1
	v_bfe_u32 v33, v30, 16, 1
	v_bfe_u32 v32, v29, 16, 1
	v_bfe_u32 v34, v31, 16, 1
	v_add3_u32 v27, v28, v27, s15
	v_add3_u32 v33, v30, v33, s15
	v_add3_u32 v32, v29, v32, s15
	v_add3_u32 v34, v31, v34, s15
	v_lshrrev_b32_e32 v27, 16, v27
	v_lshrrev_b32_e32 v33, 16, v33
	v_and_or_b32 v32, v32, s29, v27
	v_and_or_b32 v33, v34, s29, v33
	global_store_dwordx2 v[44:45], v[32:33], off
	global_load_dwordx4 v[32:35], v[40:41], off offset:1024 nt
	v_mul_f32_e32 v29, v29, v29
	v_mul_f32_e32 v31, v31, v31
	v_fmac_f32_e32 v29, v28, v28
	v_fmac_f32_e32 v31, v30, v30
	v_add_f32_e32 v28, v29, v31
	s_waitcnt vmcnt(0) lgkmcnt(0)
	v_bfe_u32 v27, v32, 16, 1
	v_bfe_u32 v37, v34, 16, 1
	v_bfe_u32 v36, v33, 16, 1
	v_bfe_u32 v38, v35, 16, 1
	v_add3_u32 v27, v32, v27, s15
	v_add3_u32 v37, v34, v37, s15
	v_add3_u32 v36, v33, v36, s15
	v_add3_u32 v38, v35, v38, s15
	v_lshrrev_b32_e32 v27, 16, v27
	v_lshrrev_b32_e32 v37, 16, v37
	v_and_or_b32 v36, v36, s29, v27
	v_and_or_b32 v37, v38, s29, v37
	global_store_dwordx2 v[44:45], v[36:37], off offset:512
	global_load_dwordx4 v[36:39], v[40:41], off offset:2048 nt
	v_mul_f32_e32 v29, v33, v33
	v_mul_f32_e32 v30, v35, v35
	v_fmac_f32_e32 v29, v32, v32
	v_fmac_f32_e32 v30, v34, v34
	v_add_f32_e32 v29, v29, v30
	v_add_f32_e32 v28, v28, v29
	s_waitcnt vmcnt(0) lgkmcnt(0)
	v_bfe_u32 v27, v36, 16, 1
	v_bfe_u32 v43, v38, 16, 1
	v_bfe_u32 v42, v37, 16, 1
	v_bfe_u32 v46, v39, 16, 1
	v_add3_u32 v27, v36, v27, s15
	v_add3_u32 v43, v38, v43, s15
	v_add3_u32 v42, v37, v42, s15
	v_add3_u32 v46, v39, v46, s15
	v_lshrrev_b32_e32 v27, 16, v27
	v_lshrrev_b32_e32 v43, 16, v43
	v_and_or_b32 v42, v42, s29, v27
	v_and_or_b32 v43, v46, s29, v43
	global_store_dwordx2 v[44:45], v[42:43], off offset:1024
	global_load_dwordx4 v[40:43], v[40:41], off offset:3072 nt
	v_mul_f32_e32 v29, v37, v37
	v_mul_f32_e32 v30, v39, v39
	v_fmac_f32_e32 v29, v36, v36
	v_fmac_f32_e32 v30, v38, v38
	v_add_f32_e32 v29, v29, v30
	v_add_f32_e32 v28, v28, v29
	v_cndmask_b32_e32 v27, v7, v21, vcc
	v_lshlrev_b32_e32 v27, 2, v27
	v_cmp_lt_i32_e32 vcc, v22, v20
	s_waitcnt vmcnt(0) lgkmcnt(0)
	v_mul_f32_e32 v29, v41, v41
	v_mul_f32_e32 v30, v43, v43
	v_fmac_f32_e32 v29, v40, v40
	v_fmac_f32_e32 v30, v42, v42
	v_add_f32_e32 v29, v29, v30
	v_add_f32_e32 v28, v28, v29
	ds_bpermute_b32 v27, v27, v28
	v_cndmask_b32_e32 v29, v7, v22, vcc
	v_lshlrev_b32_e32 v29, 2, v29
	v_cmp_lt_i32_e32 vcc, v23, v20
	v_bfe_u32 v33, v42, 16, 1
	s_waitcnt lgkmcnt(0)
	v_add_f32_e32 v27, v28, v27
	ds_bpermute_b32 v28, v29, v27
	v_cndmask_b32_e32 v30, v7, v23, vcc
	v_lshlrev_b32_e32 v30, 2, v30
	v_cmp_lt_i32_e32 vcc, v24, v20
	s_waitcnt lgkmcnt(0)
	v_add_f32_e32 v27, v27, v28
	ds_bpermute_b32 v28, v30, v27
	v_cndmask_b32_e32 v29, v7, v24, vcc
	v_lshlrev_b32_e32 v29, 2, v29
	v_cmp_lt_i32_e32 vcc, v25, v20
	s_waitcnt lgkmcnt(0)
	v_add_f32_e32 v27, v27, v28
	ds_bpermute_b32 v28, v29, v27
	v_cndmask_b32_e32 v31, v7, v25, vcc
	v_lshlrev_b32_e32 v30, 2, v31
	v_cmp_lt_i32_e32 vcc, v26, v20
	v_bfe_u32 v31, v40, 16, 1
	s_waitcnt lgkmcnt(0)
	v_add_f32_e32 v27, v27, v28
	ds_bpermute_b32 v28, v30, v27
	v_cndmask_b32_e32 v32, v7, v26, vcc
	v_bfe_u32 v29, v41, 16, 1
	v_add3_u32 v31, v40, v31, s15
	v_add3_u32 v29, v41, v29, s15
	s_waitcnt lgkmcnt(0)
	v_add_f32_e32 v27, v27, v28
	v_lshlrev_b32_e32 v28, 2, v32
	ds_bpermute_b32 v28, v28, v27
	v_add3_u32 v30, v42, v33, s15
	v_lshrrev_b32_e32 v31, 16, v31
	v_lshrrev_b32_e32 v33, 16, v30
	v_and_or_b32 v30, v29, s29, v31
	v_bfe_u32 v29, v43, 16, 1
	v_add3_u32 v29, v43, v29, s15
	v_and_or_b32 v31, v29, s29, v33
	global_store_dwordx2 v[44:45], v[30:31], off offset:1536
	s_and_saveexec_b64 s[24:25], s[8:9]
	s_cbranch_execz .LBB0_77
	s_lshl_b64 s[36:37], s[12:13], 6
	s_waitcnt lgkmcnt(0)
	v_add_f32_e32 v27, v27, v28
	v_lshl_add_u64 v[30:31], v[8:9], 0, s[36:37]
	v_cndmask_b32_e64 v27, 0, v27, s[4:5]
	global_store_dword v[30:31], v27, off

.LBB0_78:
	s_andn2_b64 vcc, exec, s[24:25]
	s_cbranch_vccnz .LBB0_82
	v_mov_b32_e32 v27, s30
	s_waitcnt lgkmcnt(0)
	ds_read_b64 v[28:29], v27
	s_add_i32 s12, s34, 0xffffc000
	s_lshl_b64 s[24:25], s[12:13], 12
	v_cmp_lt_i32_e32 vcc, v21, v20
	s_waitcnt lgkmcnt(0)
	v_readfirstlane_b32 s17, v28
	v_readfirstlane_b32 s35, v29
	s_add_u32 s24, s17, s24
	s_addc_u32 s25, s35, s25
	v_lshl_add_u64 v[40:41], s[24:25], 0, v[2:3]
	global_load_dwordx4 v[28:31], v[40:41], off nt
	s_mov_b32 s17, s13
	v_lshl_add_u64 v[44:45], v[10:11], 0, s[16:17]
	s_waitcnt vmcnt(0) lgkmcnt(0)
	v_bfe_u32 v27, v28, 16, 1
	v_bfe_u32 v33, v30, 16, 1
	v_bfe_u32 v32, v29, 16, 1
	v_bfe_u32 v34, v31, 16, 1
	v_add3_u32 v27, v28, v27, s15
	v_add3_u32 v33, v30, v33, s15
	v_add3_u32 v32, v29, v32, s15
	v_add3_u32 v34, v31, v34, s15
	v_lshrrev_b32_e32 v27, 16, v27
	v_lshrrev_b32_e32 v33, 16, v33
	v_and_or_b32 v32, v32, s29, v27
	v_and_or_b32 v33, v34, s29, v33
	global_store_dwordx2 v[44:45], v[32:33], off
	global_load_dwordx4 v[32:35], v[40:41], off offset:1024 nt
	v_mul_f32_e32 v29, v29, v29
	v_mul_f32_e32 v31, v31, v31
	v_fmac_f32_e32 v29, v28, v28
	v_fmac_f32_e32 v31, v30, v30
	v_add_f32_e32 v28, v29, v31
	s_waitcnt vmcnt(0) lgkmcnt(0)
	v_bfe_u32 v27, v32, 16, 1
	v_bfe_u32 v37, v34, 16, 1
	v_bfe_u32 v36, v33, 16, 1
	v_bfe_u32 v38, v35, 16, 1
	v_add3_u32 v27, v32, v27, s15
	v_add3_u32 v37, v34, v37, s15
	v_add3_u32 v36, v33, v36, s15
	v_add3_u32 v38, v35, v38, s15
	v_lshrrev_b32_e32 v27, 16, v27
	v_lshrrev_b32_e32 v37, 16, v37
	v_and_or_b32 v36, v36, s29, v27
	v_and_or_b32 v37, v38, s29, v37
	global_store_dwordx2 v[44:45], v[36:37], off offset:512
	global_load_dwordx4 v[36:39], v[40:41], off offset:2048 nt
	v_mul_f32_e32 v29, v33, v33
	v_mul_f32_e32 v30, v35, v35
	v_fmac_f32_e32 v29, v32, v32
	v_fmac_f32_e32 v30, v34, v34
	v_add_f32_e32 v29, v29, v30
	v_add_f32_e32 v28, v28, v29
	s_waitcnt vmcnt(0) lgkmcnt(0)
	v_bfe_u32 v27, v36, 16, 1
	v_bfe_u32 v43, v38, 16, 1
	v_bfe_u32 v42, v37, 16, 1
	v_bfe_u32 v46, v39, 16, 1
	v_add3_u32 v27, v36, v27, s15
	v_add3_u32 v43, v38, v43, s15
	v_add3_u32 v42, v37, v42, s15
	v_add3_u32 v46, v39, v46, s15
	v_lshrrev_b32_e32 v27, 16, v27
	v_lshrrev_b32_e32 v43, 16, v43
	v_and_or_b32 v42, v42, s29, v27
	v_and_or_b32 v43, v46, s29, v43
	global_store_dwordx2 v[44:45], v[42:43], off offset:1024
	global_load_dwordx4 v[40:43], v[40:41], off offset:3072 nt
	v_mul_f32_e32 v29, v37, v37
	v_mul_f32_e32 v30, v39, v39
	v_fmac_f32_e32 v29, v36, v36
	v_fmac_f32_e32 v30, v38, v38
	v_add_f32_e32 v29, v29, v30
	v_add_f32_e32 v28, v28, v29
	v_cndmask_b32_e32 v27, v7, v21, vcc
	v_lshlrev_b32_e32 v27, 2, v27
	v_cmp_lt_i32_e32 vcc, v22, v20
	s_waitcnt vmcnt(0) lgkmcnt(0)
	v_mul_f32_e32 v29, v41, v41
	v_mul_f32_e32 v30, v43, v43
	v_fmac_f32_e32 v29, v40, v40
	v_fmac_f32_e32 v30, v42, v42
	v_add_f32_e32 v29, v29, v30
	v_add_f32_e32 v28, v28, v29
	ds_bpermute_b32 v27, v27, v28
	v_cndmask_b32_e32 v29, v7, v22, vcc
	v_lshlrev_b32_e32 v29, 2, v29
	v_cmp_lt_i32_e32 vcc, v23, v20
	v_bfe_u32 v33, v42, 16, 1
	s_waitcnt lgkmcnt(0)
	v_add_f32_e32 v27, v28, v27
	ds_bpermute_b32 v28, v29, v27
	v_cndmask_b32_e32 v30, v7, v23, vcc
	v_lshlrev_b32_e32 v30, 2, v30
	v_cmp_lt_i32_e32 vcc, v24, v20
	s_waitcnt lgkmcnt(0)
	v_add_f32_e32 v27, v27, v28
	ds_bpermute_b32 v28, v30, v27
	v_cndmask_b32_e32 v29, v7, v24, vcc
	v_lshlrev_b32_e32 v29, 2, v29
	v_cmp_lt_i32_e32 vcc, v25, v20
	s_waitcnt lgkmcnt(0)
	v_add_f32_e32 v27, v27, v28
	ds_bpermute_b32 v28, v29, v27
	v_cndmask_b32_e32 v31, v7, v25, vcc
	v_lshlrev_b32_e32 v30, 2, v31
	v_cmp_lt_i32_e32 vcc, v26, v20
	v_bfe_u32 v31, v40, 16, 1
	s_waitcnt lgkmcnt(0)
	v_add_f32_e32 v27, v27, v28
	ds_bpermute_b32 v28, v30, v27
	v_cndmask_b32_e32 v32, v7, v26, vcc
	v_bfe_u32 v29, v41, 16, 1
	v_add3_u32 v31, v40, v31, s15
	v_add3_u32 v29, v41, v29, s15
	s_waitcnt lgkmcnt(0)
	v_add_f32_e32 v27, v27, v28
	v_lshlrev_b32_e32 v28, 2, v32
	ds_bpermute_b32 v28, v28, v27
	v_add3_u32 v30, v42, v33, s15
	v_lshrrev_b32_e32 v31, 16, v31
	v_lshrrev_b32_e32 v33, 16, v30
	v_and_or_b32 v30, v29, s29, v31
	v_bfe_u32 v29, v43, 16, 1
	v_add3_u32 v29, v43, v29, s15
	v_and_or_b32 v31, v29, s29, v33
	global_store_dwordx2 v[44:45], v[30:31], off offset:1536
	s_and_saveexec_b64 s[24:25], s[6:7]
	s_cbranch_execz .LBB0_81
	s_lshl_b64 s[36:37], s[12:13], 7
	s_waitcnt lgkmcnt(0)
	v_add_f32_e32 v27, v27, v28
	v_lshl_add_u64 v[30:31], v[12:13], 0, s[36:37]
	v_cndmask_b32_e64 v27, 0, v27, s[4:5]
	global_store_dword v[30:31], v27, off

.LBB0_83:
	s_andn2_b64 vcc, exec, s[24:25]
	s_cbranch_vccnz .LBB0_72
	v_mov_b32_e32 v27, s31
	s_waitcnt lgkmcnt(0)
	ds_read_b64 v[28:29], v27
	v_lshl_add_u64 v[32:33], s[10:11], 0, v[16:17]
	v_add_co_u32_e32 v44, vcc, s33, v32
	s_waitcnt lgkmcnt(0)
	v_readfirstlane_b32 s24, v28
	v_readfirstlane_b32 s25, v29
	v_addc_co_u32_e32 v45, vcc, 0, v33, vcc
	s_nop 0
	v_lshl_add_u64 v[40:41], s[24:25], 0, v[18:19]
	global_load_dwordx4 v[28:31], v[40:41], off nt
	v_cmp_lt_i32_e32 vcc, v21, v20
	s_waitcnt vmcnt(0) lgkmcnt(0)
	v_bfe_u32 v27, v28, 16, 1
	v_bfe_u32 v33, v30, 16, 1
	v_bfe_u32 v32, v29, 16, 1
	v_bfe_u32 v34, v31, 16, 1
	v_add3_u32 v27, v28, v27, s15
	v_add3_u32 v33, v30, v33, s15
	v_add3_u32 v32, v29, v32, s15
	v_add3_u32 v34, v31, v34, s15
	v_lshrrev_b32_e32 v27, 16, v27
	v_lshrrev_b32_e32 v33, 16, v33
	v_and_or_b32 v32, v32, s29, v27
	v_and_or_b32 v33, v34, s29, v33
	global_store_dwordx2 v[44:45], v[32:33], off
	global_load_dwordx4 v[32:35], v[40:41], off offset:1024 nt
	v_mul_f32_e32 v29, v29, v29
	v_mul_f32_e32 v31, v31, v31
	v_fmac_f32_e32 v29, v28, v28
	v_fmac_f32_e32 v31, v30, v30
	v_add_f32_e32 v28, v29, v31
	s_waitcnt vmcnt(0) lgkmcnt(0)
	v_bfe_u32 v27, v32, 16, 1
	v_bfe_u32 v37, v34, 16, 1
	v_bfe_u32 v36, v33, 16, 1
	v_bfe_u32 v38, v35, 16, 1
	v_add3_u32 v27, v32, v27, s15
	v_add3_u32 v37, v34, v37, s15
	v_add3_u32 v36, v33, v36, s15
	v_add3_u32 v38, v35, v38, s15
	v_lshrrev_b32_e32 v27, 16, v27
	v_lshrrev_b32_e32 v37, 16, v37
	v_and_or_b32 v36, v36, s29, v27
	v_and_or_b32 v37, v38, s29, v37
	global_store_dwordx2 v[44:45], v[36:37], off offset:512
	global_load_dwordx4 v[36:39], v[40:41], off offset:2048 nt
	v_mul_f32_e32 v29, v33, v33
	v_mul_f32_e32 v30, v35, v35
	v_fmac_f32_e32 v29, v32, v32
	v_fmac_f32_e32 v30, v34, v34
	v_add_f32_e32 v29, v29, v30
	v_add_f32_e32 v28, v28, v29
	s_waitcnt vmcnt(0) lgkmcnt(0)
	v_bfe_u32 v27, v36, 16, 1
	v_bfe_u32 v43, v38, 16, 1
	v_bfe_u32 v42, v37, 16, 1
	v_bfe_u32 v46, v39, 16, 1
	v_add3_u32 v27, v36, v27, s15
	v_add3_u32 v43, v38, v43, s15
	v_add3_u32 v42, v37, v42, s15
	v_add3_u32 v46, v39, v46, s15
	v_lshrrev_b32_e32 v27, 16, v27
	v_lshrrev_b32_e32 v43, 16, v43
	v_and_or_b32 v42, v42, s29, v27
	v_and_or_b32 v43, v46, s29, v43
	global_store_dwordx2 v[44:45], v[42:43], off offset:1024
	global_load_dwordx4 v[40:43], v[40:41], off offset:3072 nt
	v_mul_f32_e32 v29, v37, v37
	v_mul_f32_e32 v30, v39, v39
	v_fmac_f32_e32 v29, v36, v36
	v_fmac_f32_e32 v30, v38, v38
	v_add_f32_e32 v29, v29, v30
	v_add_f32_e32 v28, v28, v29
	v_cndmask_b32_e32 v27, v7, v21, vcc
	v_lshlrev_b32_e32 v27, 2, v27
	v_cmp_lt_i32_e32 vcc, v22, v20
	s_waitcnt vmcnt(0) lgkmcnt(0)
	v_mul_f32_e32 v29, v41, v41
	v_mul_f32_e32 v30, v43, v43
	v_fmac_f32_e32 v29, v40, v40
	v_fmac_f32_e32 v30, v42, v42
	v_add_f32_e32 v29, v29, v30
	v_add_f32_e32 v28, v28, v29
	ds_bpermute_b32 v27, v27, v28
	v_cndmask_b32_e32 v29, v7, v22, vcc
	v_lshlrev_b32_e32 v29, 2, v29
	v_cmp_lt_i32_e32 vcc, v23, v20
	v_bfe_u32 v33, v42, 16, 1
	s_waitcnt lgkmcnt(0)
	v_add_f32_e32 v27, v28, v27
	ds_bpermute_b32 v28, v29, v27
	v_cndmask_b32_e32 v30, v7, v23, vcc
	v_lshlrev_b32_e32 v30, 2, v30
	v_cmp_lt_i32_e32 vcc, v24, v20
	s_waitcnt lgkmcnt(0)
	v_add_f32_e32 v27, v27, v28
	ds_bpermute_b32 v28, v30, v27
	v_cndmask_b32_e32 v29, v7, v24, vcc
	v_lshlrev_b32_e32 v29, 2, v29
	v_cmp_lt_i32_e32 vcc, v25, v20
	s_waitcnt lgkmcnt(0)
	v_add_f32_e32 v27, v27, v28
	ds_bpermute_b32 v28, v29, v27
	v_cndmask_b32_e32 v31, v7, v25, vcc
	v_lshlrev_b32_e32 v30, 2, v31
	v_cmp_lt_i32_e32 vcc, v26, v20
	v_bfe_u32 v31, v40, 16, 1
	s_waitcnt lgkmcnt(0)
	v_add_f32_e32 v27, v27, v28
	ds_bpermute_b32 v28, v30, v27
	v_cndmask_b32_e32 v32, v7, v26, vcc
	v_bfe_u32 v29, v41, 16, 1
	v_add3_u32 v31, v40, v31, s15
	v_add3_u32 v29, v41, v29, s15
	s_waitcnt lgkmcnt(0)
	v_add_f32_e32 v27, v27, v28
	v_lshlrev_b32_e32 v28, 2, v32
	ds_bpermute_b32 v28, v28, v27
	v_add3_u32 v30, v42, v33, s15
	v_lshrrev_b32_e32 v31, 16, v31
	v_lshrrev_b32_e32 v33, 16, v30
	v_and_or_b32 v30, v29, s29, v31
	v_bfe_u32 v29, v43, 16, 1
	v_add3_u32 v29, v43, v29, s15
	v_and_or_b32 v31, v29, s29, v33
	global_store_dwordx2 v[44:45], v[30:31], off offset:1536
	s_and_saveexec_b64 s[24:25], s[8:9]
	s_cbranch_execz .LBB0_71
	s_waitcnt lgkmcnt(0)
	v_add_f32_e32 v27, v27, v28
	v_lshl_add_u64 v[30:31], s[10:11], 0, v[14:15]
	v_cndmask_b32_e64 v27, 0, v27, s[4:5]
	global_store_dword v[30:31], v27, off
	s_branch .LBB0_71
